# v55 + attention: wave 0 warms L2 with the next queued unit's Q rows and gate rows while the current unit runs (cross-unit prefetch)
# baseline (speedup 1.0000x reference)
.LBB0_550:
	s_or_b64 exec, exec, s[0:1]
	v_add_u32_e32 v0, 1, v128
	v_cvt_f32_u32_e32 v0, v0
	v_mov_b32_e32 v95, v97
	v_mov_b32_e32 v97, v103
	v_mov_b32_e32 v79, v85
	v_exp_f32_e64 v0, -v0
	v_mov_b32_e32 v85, v101
	v_mov_b32_e32 v87, v93
	v_mov_b32_e32 v93, v113
	v_mul_f32_e32 v118, 0x3fb8aa3b, v0
	v_add_f32_e32 v0, v99, v102
	v_fmamk_f32 v0, v0, 0x3c800000, v154
	v_rsq_f32_e32 v0, v0
	v_mov_b32_e32 v99, v67
	v_mov_b32_e32 v77, v89
	v_mov_b32_e32 v89, v117
	v_mul_f32_e32 v0, 0x3e38aa3b, v0
	s_waitcnt vmcnt(0)
	v_readfirstlane_b32 s0, v202
	s_cmp_lt_u32 s0, 64
	s_cbranch_scc0 .Lpf_end
	s_cmp_eq_u32 s88, 0x100
	s_cbranch_scc0 .Lpf_end
	v_readfirstlane_b32 s0, v164
	v_readlane_b32 s3, v248, 5
	s_cmp_ge_u32 s0, 0xa0
	s_cbranch_scc1 .Lpf_end
	s_mul_hi_u32 s1, s0, 0xcccccccd
	s_lshr_b32 s1, s1, 2
	s_mul_i32 s2, s1, 5
	s_sub_i32 s2, s0, s2
	s_cmp_eq_u32 s2, 4
	s_cbranch_scc1 .Lpf_end
	s_lshl_b32 s1, s1, 2
	s_add_i32 s1, s1, s2
	s_and_b32 s3, s3, 7
	s_lshl_b32 s1, s1, 3
	s_or_b32 s1, s1, s3
	s_lshr_b32 s4, s1, 3
	s_sub_i32 s5, 63, s4
	s_mov_b32 s6, 1
	s_cmpk_lt_u32 s1, 0x170
	s_cbranch_scc1 .Lpf_dec
	s_sub_i32 s5, s1, 0x170
	s_lshr_b32 s5, s5, 3
	s_sub_i32 s5, 63, s5
	s_mov_b32 s6, 0
	s_cmpk_lt_u32 s1, 0x2e8
	s_cbranch_scc1 .Lpf_dec
	s_mov_b32 s5, 17
	s_mov_b32 s6, 1
	s_cmpk_lt_u32 s1, 0x2f0
	s_cbranch_scc1 .Lpf_dec
	s_sub_i32 s5, s1, 0x2f0
	s_lshr_b32 s5, s5, 4
	s_sub_i32 s5, 16, s5
	s_bfe_u32 s6, s1, 0x10003
.Lpf_dec:
	s_lshl_b32 s3, s3, 12
	s_lshl_b32 s5, s5, 6
	s_add_i32 s3, s3, s5
	v_and_b32_e32 v204, 63, v202
	v_add_u32_e32 v204, s3, v204
	v_lshlrev_b32_e32 v206, 6, v204
	v_lshlrev_b32_e32 v204, 10, v204
	s_lshl_b32 s6, s6, 9
	v_add_u32_e32 v204, s6, v204
	v_readlane_b32 s4, v249, 39
	v_readlane_b32 s5, v249, 40
	v_readlane_b32 s6, v249, 27
	v_readlane_b32 s7, v249, 28
	s_nop 4
	global_load_dword v205, v204, s[4:5]
	global_load_dword v205, v204, s[4:5] offset:128
	global_load_dword v205, v204, s[4:5] offset:256
	global_load_dword v205, v204, s[4:5] offset:384
	global_load_dword v205, v206, s[6:7]
